# P0 x->bf16 row loop software-pipelined: next row loads issued before current row stores, counted vmcnt(3)
# baseline (speedup 1.0000x reference)
; #define GAS __attribute__((address_space(1)))
; __device__ __forceinline__ void row_to_bf16_ss(const float* xrow, bf16_t* orow, float* ssrow, int lane) {
;     const GAS f32x4* xr = (const GAS f32x4*)xrow + 2 * lane;
;     f32x4 v[4]; float s = 0.f;
; #pragma unroll
;     for (int j = 0; j < 2; ++j) { v[2 * j] = xr[128 * j]; v[2 * j + 1] = xr[128 * j + 1]; }
; #pragma unroll
;     for (int j = 0; j < 4; ++j) s += (v[j].x * v[j].x + v[j].y * v[j].y) + (v[j].z * v[j].z + v[j].w * v[j].w);
;     s = wave_sum(s);
;     GAS u32x4* o16 = (GAS u32x4*)orow + lane;
; __global__ void __launch_bounds__(512, 2) fwd_mega(Params P) {
;     ...
;         for (int mrow = gw; mrow < M; mrow += NGW) row_to_bf16_ss(P.in[0] + (size_t)mrow * D, XB + (size_t)mrow * D, SS + (size_t)mrow * 16, lane);
.LBB0_186:
	s_cmp_gt_i32 s30, 0xffff
	v_mbcnt_lo_u32_b32 v204, -1, 0
	s_cbranch_scc1 .LBB0_191
	v_mbcnt_hi_u32_b32 v5, -1, v204
	v_and_b32_e32 v1, 64, v5
	v_add_u32_e32 v6, 64, v1
	v_xor_b32_e32 v1, 1, v5
	v_cmp_lt_i32_e32 vcc, v1, v6
	v_xor_b32_e32 v3, 2, v5
	v_xor_b32_e32 v7, 4, v5
	v_cndmask_b32_e32 v1, v5, v1, vcc
	v_cmp_lt_i32_e32 vcc, v3, v6
	s_ashr_i32 s31, s30, 31
	s_lshl_b64 s[6:7], s[30:31], 6
	v_cndmask_b32_e32 v3, v5, v3, vcc
	v_cmp_lt_i32_e32 vcc, v7, v6
	s_add_u32 s6, s34, s6
	v_mov_b32_e32 v13, 0
	v_cndmask_b32_e32 v7, v5, v7, vcc
	v_lshlrev_b32_e32 v8, 2, v7
	v_xor_b32_e32 v7, 8, v5
	v_cmp_lt_i32_e32 vcc, v7, v6
	v_lshlrev_b32_e32 v12, 2, v2
	s_addc_u32 s7, s35, s7
	v_cndmask_b32_e32 v7, v5, v7, vcc
	v_lshlrev_b32_e32 v9, 2, v7
	v_xor_b32_e32 v7, 16, v5
	v_cmp_lt_i32_e32 vcc, v7, v6
	v_readlane_b32 s4, v254, 2
	v_readlane_b32 s5, v254, 3
	v_cndmask_b32_e32 v7, v5, v7, vcc
	v_lshlrev_b32_e32 v10, 2, v7
	v_xor_b32_e32 v7, 32, v5
	v_cmp_lt_i32_e32 vcc, v7, v6
	s_load_dwordx2 s[12:13], s[4:5], 0x0
	s_lshl_b64 s[8:9], s[30:31], 11
	v_cndmask_b32_e32 v5, v5, v7, vcc
	v_lshl_add_u64 v[6:7], s[6:7], 0, v[12:13]
	s_mov_b64 s[6:7], 0x2d000000
	v_lshl_add_u64 v[6:7], v[6:7], 0, s[6:7]
	v_readlane_b32 s6, v254, 4
	v_readlane_b32 s7, v254, 5
	s_mov_b32 s16, s6
	s_ashr_i32 s17, s6, 31
	s_lshl_b64 s[6:7], s[16:17], 6
	s_add_u32 s3, s34, s8
	s_addc_u32 s9, s35, s9
	s_add_u32 s8, s3, 0x25000000
	s_addc_u32 s9, s9, 0
	s_lshl_b64 s[10:11], s[16:17], 11
	s_lshl_b64 s[14:15], s[30:31], 12
	s_waitcnt lgkmcnt(0)
	s_add_u32 s12, s12, s14
	v_lshlrev_b32_e32 v11, 2, v5
	v_mov_b32_e32 v5, v13
	s_addc_u32 s13, s13, s15
	v_lshl_add_u64 v[4:5], s[12:13], 0, v[4:5]
	s_mov_b64 s[12:13], 0x810
	v_lshl_add_u64 v[4:5], v[4:5], 0, s[12:13]
	s_mov_b32 s12, s16
	v_writelane_b32 v254, s12, 4
	v_lshlrev_b32_e32 v1, 2, v1
	v_lshlrev_b32_e32 v3, 2, v3
	v_cmp_gt_u32_e32 vcc, 16, v2
	v_cmp_eq_u32_e64 s[4:5], 0, v2
	v_writelane_b32 v254, s13, 5
	s_lshl_b64 s[12:13], s[16:17], 12
	v_lshlrev_b32_e32 v2, 4, v2
	global_load_dwordx4 v[36:39], v[4:5], off offset:-2064
	global_load_dwordx4 v[40:43], v[4:5], off offset:-2048
	global_load_dwordx4 v[44:47], v[4:5], off offset:-16
	global_load_dwordx4 v[48:51], v[4:5], off
	s_waitcnt vmcnt(0)
	s_branch .LBB0_189

; __device__ __forceinline__ unsigned pk2(float lo, float hi) { f32x2_t v = {lo, hi}; bf16x2_t b = __builtin_convertvector(v, bf16x2_t); return __builtin_bit_cast(unsigned, b); }
; #define GAS __attribute__((address_space(1)))
; __device__ __forceinline__ void row_to_bf16_ss(const float* xrow, bf16_t* orow, float* ssrow, int lane) {
;     const GAS f32x4* xr = (const GAS f32x4*)xrow + 2 * lane;
;     f32x4 v[4]; float s = 0.f;
; #pragma unroll
;     for (int j = 0; j < 2; ++j) { v[2 * j] = xr[128 * j]; v[2 * j + 1] = xr[128 * j + 1]; }
; #pragma unroll
;     for (int j = 0; j < 4; ++j) s += (v[j].x * v[j].x + v[j].y * v[j].y) + (v[j].z * v[j].z + v[j].w * v[j].w);
;     s = wave_sum(s);
;     GAS u32x4* o16 = (GAS u32x4*)orow + lane;
; #pragma unroll
;     for (int j = 0; j < 2; ++j) { u32x4 w; w.x = pk2(v[2 * j].x, v[2 * j].y); w.y = pk2(v[2 * j].z, v[2 * j].w); w.z = pk2(v[2 * j + 1].x, v[2 * j + 1].y); w.w = pk2(v[2 * j + 1].z, v[2 * j + 1].w); o16[64 * j] = w; }
;     if (lane < 16) *(GAS float*)(ssrow + lane) = (lane == 0) ? s : 0.f;
; }
.LBB0_189:
	s_waitcnt lgkmcnt(0)
	s_waitcnt vmcnt(3)
	v_mov_b64_e32 v[12:13], v[36:37]
	v_mov_b64_e32 v[14:15], v[38:39]
	v_mov_b64_e32 v[16:17], v[40:41]
	v_mov_b64_e32 v[18:19], v[42:43]
	v_mov_b64_e32 v[20:21], v[44:45]
	v_mov_b64_e32 v[22:23], v[46:47]
	v_mov_b64_e32 v[24:25], v[48:49]
	v_mov_b64_e32 v[26:27], v[50:51]
	v_readlane_b32 s100, v254, 4
	s_nop 0
	s_add_i32 s100, s30, s100
	s_cmp_gt_i32 s100, 0xffff
	s_cbranch_scc1 .Lp0_nopre
	v_lshl_add_u64 v[52:53], v[4:5], 0, s[12:13]
	global_load_dwordx4 v[36:39], v[52:53], off offset:-2064
	global_load_dwordx4 v[40:43], v[52:53], off offset:-2048
	global_load_dwordx4 v[44:47], v[52:53], off offset:-16
	global_load_dwordx4 v[48:51], v[52:53], off
.Lp0_nopre:
	v_mul_f32_e32 v28, v13, v13
	v_mul_f32_e32 v29, v15, v15
	v_mul_f32_e32 v30, v17, v17
	v_mul_f32_e32 v31, v19, v19
	v_mul_f32_e32 v32, v21, v21
	v_mul_f32_e32 v33, v23, v23
	v_fmac_f32_e32 v28, v12, v12
	v_fmac_f32_e32 v29, v14, v14
	v_fmac_f32_e32 v30, v16, v16
	v_fmac_f32_e32 v31, v18, v18
	v_mul_f32_e32 v34, v25, v25
	v_mul_f32_e32 v35, v27, v27
	v_fmac_f32_e32 v32, v20, v20
	v_fmac_f32_e32 v33, v22, v22
	v_add_f32_e32 v28, v28, v29
	v_add_f32_e32 v29, v30, v31
	v_fmac_f32_e32 v34, v24, v24
	v_fmac_f32_e32 v35, v26, v26
	v_add_f32_e32 v30, v32, v33
	v_add_f32_e32 v28, v28, v29
	v_add_f32_e32 v31, v34, v35
	v_add_f32_e32 v28, v28, v30
	v_add_f32_e32 v28, v28, v31
	ds_bpermute_b32 v29, v1, v28
	v_cvt_pk_bf16_f32 v12, v12, v13
	v_cvt_pk_bf16_f32 v13, v14, v15
	v_cvt_pk_bf16_f32 v14, v16, v17
	v_cvt_pk_bf16_f32 v15, v18, v19
	s_waitcnt lgkmcnt(0)
	v_add_f32_e32 v28, v28, v29
	ds_bpermute_b32 v29, v3, v28
	global_store_dwordx4 v2, v[12:15], s[8:9]
	v_cvt_pk_bf16_f32 v16, v24, v25
	v_cvt_pk_bf16_f32 v17, v26, v27
	v_cvt_pk_bf16_f32 v14, v20, v21
	s_waitcnt lgkmcnt(0)
	v_add_f32_e32 v28, v28, v29
	ds_bpermute_b32 v29, v8, v28
	v_cvt_pk_bf16_f32 v15, v22, v23
	global_store_dwordx4 v2, v[14:17], s[8:9] offset:1024
	s_waitcnt lgkmcnt(0)
	v_add_f32_e32 v28, v28, v29
	ds_bpermute_b32 v29, v9, v28
	s_waitcnt lgkmcnt(0)
	v_add_f32_e32 v28, v28, v29
	ds_bpermute_b32 v29, v10, v28
	s_waitcnt lgkmcnt(0)
	v_add_f32_e32 v12, v28, v29
	ds_bpermute_b32 v13, v11, v12
	s_and_saveexec_b64 s[14:15], vcc
	s_cbranch_execz .LBB0_188
	s_waitcnt lgkmcnt(0)
	v_add_f32_e32 v12, v12, v13
	v_cndmask_b32_e64 v12, 0, v12, s[4:5]
	global_store_dword v[6:7], v12, off
	s_branch .LBB0_188
